# s5_carry scan software-pipelined: blocks of 8 chunks, loads of the next two blocks in flight (33 serialized round trips before)
# speedup vs baseline: 1.0334x; 1.0060x over previous
.LBB0_1136:
	v_readlane_b32 s2, v255, 40
	s_add_i32 s0, s2, 1
	v_readlane_b32 s3, v255, 41
	v_writelane_b32 v255, s0, 42
	s_waitcnt lgkmcnt(0)
	s_barrier
	v_writelane_b32 v255, s1, 43
	s_mov_b32 s0, s1
	s_mov_b32 s1, -1
	v_readlane_b32 s3, v255, 5
	s_mul_i32 s2, s3, s0
	v_mbcnt_lo_u32_b32 v0, s1, 0
	v_readlane_b32 s4, v253, 2
	s_lshl_b32 s0, s0, 14
	v_mbcnt_hi_u32_b32 v0, s1, v0
	s_add_i32 s87, s2, s46
	v_readlane_b32 s5, v253, 3
	v_readlane_b32 s6, v253, 4
	v_readlane_b32 s7, v253, 5
	s_add_i32 s86, s0, 0
	v_and_b32_e32 v224, 63, v0
	s_mov_b64 s[12:13], s[6:7]
	s_mov_b64 s[10:11], s[4:5]
	s_cmpk_gt_i32 s87, 0xff
	s_mov_b64 s[0:1], -1
	s_cbranch_scc0 .LBB0_1315
	s_add_i32 s95, s87, 0xffffff00
	s_cmpk_gt_u32 s87, 0x17f
	s_cbranch_scc1 .LBB0_1147
	s_lshr_b32 s38, s95, 5
	s_and_b32 s0, s87, 31
	v_readlane_b32 s4, v255, 52
	v_readlane_b32 s5, v255, 53
	s_add_u32 s1, s12, s4
	s_addc_u32 s5, s13, s5
	s_lshl_b32 s4, s0, 9
	s_add_u32 s4, s1, s4
	v_lshlrev_b32_e32 v0, 1, v224
	s_addc_u32 s5, s5, 0
	v_ashrrev_i32_e32 v1, 31, v0
	v_lshl_add_u64 v[0:1], v[0:1], 2, s[4:5]
	s_mov_b32 s1, 0x399f2000
	v_add_co_u32_e32 v0, vcc, s1, v0
	s_mul_i32 s4, s38, 0x280000
	s_nop 0
	v_addc_co_u32_e32 v1, vcc, 0, v1, vcc
	global_load_dwordx2 v[0:1], v[0:1], off
	s_mul_i32 s5, s0, 0x14000
	s_mul_hi_u32 s1, s38, 0x280000
	s_add_u32 s4, s4, s5
	s_addc_u32 s1, s1, 0
	s_add_u32 s4, s12, s4
	v_ashrrev_i32_e32 v225, 31, v224
	s_addc_u32 s5, s13, s1
	v_lshl_add_u64 v[4:5], v[224:225], 2, s[4:5]
	s_mov_b64 s[4:5], 0x39a02400
	v_lshl_add_u64 v[4:5], v[4:5], 0, s[4:5]
	s_mul_i32 s4, s38, 0x140000
	s_mul_i32 s5, s0, 0xa000
	s_mul_hi_u32 s1, s38, 0x140000
	s_add_u32 s4, s4, s5
	s_addc_u32 s1, s1, 0
	s_add_u32 s4, s12, s4
	s_addc_u32 s5, s13, s1
	v_lshl_add_u64 v[6:7], v[224:225], 1, s[4:5]
	s_mov_b64 s[4:5], 0x3a402200
	v_lshl_add_u64 v[6:7], v[6:7], 0, s[4:5]
	v_mov_b32_e32 v10, 0
	s_mov_b32 s1, -4
	v_mov_b32_e32 v8, 0
	s_waitcnt vmcnt(0)
	v_pk_mov_b32 v[2:3], v[0:1], v[0:1] op_sel:[1,0]
	v_mov_b32_e32 v9, 0
	s_mov_b64 s[100:101], 0x1000
	v_mov_b64_e32 v[148:149], v[4:5]
	global_load_dword v101, v[148:149], off offset:-1024
	global_load_dword v100, v[148:149], off offset:-768
	global_load_dword v103, v[148:149], off offset:-512
	global_load_dword v102, v[148:149], off offset:-256
	global_load_dword v105, v[148:149], off
	global_load_dword v104, v[148:149], off offset:256
	global_load_dword v107, v[148:149], off offset:512
	global_load_dword v106, v[148:149], off offset:768
	global_load_dword v109, v[148:149], off offset:1024
	global_load_dword v108, v[148:149], off offset:1280
	global_load_dword v111, v[148:149], off offset:1536
	global_load_dword v110, v[148:149], off offset:1792
	global_load_dword v113, v[148:149], off offset:2048
	global_load_dword v112, v[148:149], off offset:2304
	global_load_dword v115, v[148:149], off offset:2560
	global_load_dword v114, v[148:149], off offset:2816
	v_lshl_add_u64 v[148:149], v[148:149], 0, s[100:101]
	global_load_dword v117, v[148:149], off offset:-1024
	global_load_dword v116, v[148:149], off offset:-768
	global_load_dword v119, v[148:149], off offset:-512
	global_load_dword v118, v[148:149], off offset:-256
	global_load_dword v121, v[148:149], off
	global_load_dword v120, v[148:149], off offset:256
	global_load_dword v123, v[148:149], off offset:512
	global_load_dword v122, v[148:149], off offset:768
	global_load_dword v125, v[148:149], off offset:1024
	global_load_dword v124, v[148:149], off offset:1280
	global_load_dword v127, v[148:149], off offset:1536
	global_load_dword v126, v[148:149], off offset:1792
	global_load_dword v129, v[148:149], off offset:2048
	global_load_dword v128, v[148:149], off offset:2304
	global_load_dword v131, v[148:149], off offset:2560
	global_load_dword v130, v[148:149], off offset:2816
	v_lshl_add_u64 v[148:149], v[148:149], 0, s[100:101]
	global_load_dword v133, v[148:149], off offset:-1024
	global_load_dword v132, v[148:149], off offset:-768
	global_load_dword v135, v[148:149], off offset:-512
	global_load_dword v134, v[148:149], off offset:-256
	global_load_dword v137, v[148:149], off
	global_load_dword v136, v[148:149], off offset:256
	global_load_dword v139, v[148:149], off offset:512
	global_load_dword v138, v[148:149], off offset:768
	global_load_dword v141, v[148:149], off offset:1024
	global_load_dword v140, v[148:149], off offset:1280
	global_load_dword v143, v[148:149], off offset:1536
	global_load_dword v142, v[148:149], off offset:1792
	global_load_dword v145, v[148:149], off offset:2048
	global_load_dword v144, v[148:149], off offset:2304
	global_load_dword v147, v[148:149], off offset:2560
	global_load_dword v146, v[148:149], off offset:2816
	v_lshl_add_u64 v[148:149], v[148:149], 0, s[100:101]
	s_waitcnt vmcnt(32)
	v_bfe_u32 v10, v9, 16, 1
	v_add3_u32 v10, v9, v10, s48
	global_store_short_d16_hi v[6:7], v10, off offset:-512
	v_bfe_u32 v11, v8, 16, 1
	v_add3_u32 v11, v8, v11, s48
	global_store_short_d16_hi v[6:7], v11, off offset:-384
	v_pk_mul_f32 v[16:17], v[0:1], v[8:9] op_sel_hi:[1,0]
	s_nop 0
	v_pk_fma_f32 v[18:19], v[2:3], v[8:9], v[16:17] op_sel:[0,1,0]
	v_pk_fma_f32 v[8:9], v[2:3], v[8:9], v[16:17] op_sel:[0,1,0] neg_lo:[0,0,1] neg_hi:[0,0,1]
	s_nop 0
	v_mov_b32_e32 v19, v9
	v_pk_add_f32 v[8:9], v[100:101], v[18:19]
	v_bfe_u32 v10, v9, 16, 1
	v_add3_u32 v10, v9, v10, s48
	global_store_short_d16_hi v[6:7], v10, off offset:-256
	v_bfe_u32 v11, v8, 16, 1
	v_add3_u32 v11, v8, v11, s48
	global_store_short_d16_hi v[6:7], v11, off offset:-128
	v_pk_mul_f32 v[16:17], v[0:1], v[8:9] op_sel_hi:[1,0]
	s_nop 0
	v_pk_fma_f32 v[18:19], v[2:3], v[8:9], v[16:17] op_sel:[0,1,0]
	v_pk_fma_f32 v[8:9], v[2:3], v[8:9], v[16:17] op_sel:[0,1,0] neg_lo:[0,0,1] neg_hi:[0,0,1]
	s_nop 0
	v_mov_b32_e32 v19, v9
	v_pk_add_f32 v[8:9], v[102:103], v[18:19]
	v_bfe_u32 v10, v9, 16, 1
	v_add3_u32 v10, v9, v10, s48
	global_store_short_d16_hi v[6:7], v10, off
	v_bfe_u32 v11, v8, 16, 1
	v_add3_u32 v11, v8, v11, s48
	global_store_short_d16_hi v[6:7], v11, off offset:128
	v_pk_mul_f32 v[16:17], v[0:1], v[8:9] op_sel_hi:[1,0]
	s_nop 0
	v_pk_fma_f32 v[18:19], v[2:3], v[8:9], v[16:17] op_sel:[0,1,0]
	v_pk_fma_f32 v[8:9], v[2:3], v[8:9], v[16:17] op_sel:[0,1,0] neg_lo:[0,0,1] neg_hi:[0,0,1]
	s_nop 0
	v_mov_b32_e32 v19, v9
	v_pk_add_f32 v[8:9], v[104:105], v[18:19]
	v_bfe_u32 v10, v9, 16, 1
	v_add3_u32 v10, v9, v10, s48
	global_store_short_d16_hi v[6:7], v10, off offset:256
	v_bfe_u32 v11, v8, 16, 1
	v_add3_u32 v11, v8, v11, s48
	global_store_short_d16_hi v[6:7], v11, off offset:384
	v_pk_mul_f32 v[16:17], v[0:1], v[8:9] op_sel_hi:[1,0]
	s_nop 0
	v_pk_fma_f32 v[18:19], v[2:3], v[8:9], v[16:17] op_sel:[0,1,0]
	v_pk_fma_f32 v[8:9], v[2:3], v[8:9], v[16:17] op_sel:[0,1,0] neg_lo:[0,0,1] neg_hi:[0,0,1]
	s_nop 0
	v_mov_b32_e32 v19, v9
	v_pk_add_f32 v[8:9], v[106:107], v[18:19]
	v_bfe_u32 v10, v9, 16, 1
	v_add3_u32 v10, v9, v10, s48
	global_store_short_d16_hi v[6:7], v10, off offset:512
	v_bfe_u32 v11, v8, 16, 1
	v_add3_u32 v11, v8, v11, s48
	global_store_short_d16_hi v[6:7], v11, off offset:640
	v_pk_mul_f32 v[16:17], v[0:1], v[8:9] op_sel_hi:[1,0]
	s_nop 0
	v_pk_fma_f32 v[18:19], v[2:3], v[8:9], v[16:17] op_sel:[0,1,0]
	v_pk_fma_f32 v[8:9], v[2:3], v[8:9], v[16:17] op_sel:[0,1,0] neg_lo:[0,0,1] neg_hi:[0,0,1]
	s_nop 0
	v_mov_b32_e32 v19, v9
	v_pk_add_f32 v[8:9], v[108:109], v[18:19]
	v_bfe_u32 v10, v9, 16, 1
	v_add3_u32 v10, v9, v10, s48
	global_store_short_d16_hi v[6:7], v10, off offset:768
	v_bfe_u32 v11, v8, 16, 1
	v_add3_u32 v11, v8, v11, s48
	global_store_short_d16_hi v[6:7], v11, off offset:896
	v_pk_mul_f32 v[16:17], v[0:1], v[8:9] op_sel_hi:[1,0]
	s_nop 0
	v_pk_fma_f32 v[18:19], v[2:3], v[8:9], v[16:17] op_sel:[0,1,0]
	v_pk_fma_f32 v[8:9], v[2:3], v[8:9], v[16:17] op_sel:[0,1,0] neg_lo:[0,0,1] neg_hi:[0,0,1]
	s_nop 0
	v_mov_b32_e32 v19, v9
	v_pk_add_f32 v[8:9], v[110:111], v[18:19]
	v_bfe_u32 v10, v9, 16, 1
	v_add3_u32 v10, v9, v10, s48
	global_store_short_d16_hi v[6:7], v10, off offset:1024
	v_bfe_u32 v11, v8, 16, 1
	v_add3_u32 v11, v8, v11, s48
	global_store_short_d16_hi v[6:7], v11, off offset:1152
	v_pk_mul_f32 v[16:17], v[0:1], v[8:9] op_sel_hi:[1,0]
	s_nop 0
	v_pk_fma_f32 v[18:19], v[2:3], v[8:9], v[16:17] op_sel:[0,1,0]
	v_pk_fma_f32 v[8:9], v[2:3], v[8:9], v[16:17] op_sel:[0,1,0] neg_lo:[0,0,1] neg_hi:[0,0,1]
	s_nop 0
	v_mov_b32_e32 v19, v9
	v_pk_add_f32 v[8:9], v[112:113], v[18:19]
	v_bfe_u32 v10, v9, 16, 1
	v_add3_u32 v10, v9, v10, s48
	global_store_short_d16_hi v[6:7], v10, off offset:1280
	v_bfe_u32 v11, v8, 16, 1
	v_add3_u32 v11, v8, v11, s48
	global_store_short_d16_hi v[6:7], v11, off offset:1408
	v_pk_mul_f32 v[16:17], v[0:1], v[8:9] op_sel_hi:[1,0]
	s_nop 0
	v_pk_fma_f32 v[18:19], v[2:3], v[8:9], v[16:17] op_sel:[0,1,0]
	v_pk_fma_f32 v[8:9], v[2:3], v[8:9], v[16:17] op_sel:[0,1,0] neg_lo:[0,0,1] neg_hi:[0,0,1]
	s_nop 0
	v_mov_b32_e32 v19, v9
	v_pk_add_f32 v[8:9], v[114:115], v[18:19]
	v_lshl_add_u64 v[6:7], v[6:7], 0, s[84:85]
	s_mov_b32 s1, 0
.Lmy_s5c_loop:
	global_load_dword v101, v[148:149], off offset:-1024
	global_load_dword v100, v[148:149], off offset:-768
	global_load_dword v103, v[148:149], off offset:-512
	global_load_dword v102, v[148:149], off offset:-256
	global_load_dword v105, v[148:149], off
	global_load_dword v104, v[148:149], off offset:256
	global_load_dword v107, v[148:149], off offset:512
	global_load_dword v106, v[148:149], off offset:768
	global_load_dword v109, v[148:149], off offset:1024
	global_load_dword v108, v[148:149], off offset:1280
	global_load_dword v111, v[148:149], off offset:1536
	global_load_dword v110, v[148:149], off offset:1792
	global_load_dword v113, v[148:149], off offset:2048
	global_load_dword v112, v[148:149], off offset:2304
	global_load_dword v115, v[148:149], off offset:2560
	global_load_dword v114, v[148:149], off offset:2816
	v_lshl_add_u64 v[148:149], v[148:149], 0, s[100:101]
	s_waitcnt vmcnt(48)
	v_bfe_u32 v10, v9, 16, 1
	v_add3_u32 v10, v9, v10, s48
	global_store_short_d16_hi v[6:7], v10, off offset:-512
	v_bfe_u32 v11, v8, 16, 1
	v_add3_u32 v11, v8, v11, s48
	global_store_short_d16_hi v[6:7], v11, off offset:-384
	v_pk_mul_f32 v[16:17], v[0:1], v[8:9] op_sel_hi:[1,0]
	s_nop 0
	v_pk_fma_f32 v[18:19], v[2:3], v[8:9], v[16:17] op_sel:[0,1,0]
	v_pk_fma_f32 v[8:9], v[2:3], v[8:9], v[16:17] op_sel:[0,1,0] neg_lo:[0,0,1] neg_hi:[0,0,1]
	s_nop 0
	v_mov_b32_e32 v19, v9
	v_pk_add_f32 v[8:9], v[116:117], v[18:19]
	v_bfe_u32 v10, v9, 16, 1
	v_add3_u32 v10, v9, v10, s48
	global_store_short_d16_hi v[6:7], v10, off offset:-256
	v_bfe_u32 v11, v8, 16, 1
	v_add3_u32 v11, v8, v11, s48
	global_store_short_d16_hi v[6:7], v11, off offset:-128
	v_pk_mul_f32 v[16:17], v[0:1], v[8:9] op_sel_hi:[1,0]
	s_nop 0
	v_pk_fma_f32 v[18:19], v[2:3], v[8:9], v[16:17] op_sel:[0,1,0]
	v_pk_fma_f32 v[8:9], v[2:3], v[8:9], v[16:17] op_sel:[0,1,0] neg_lo:[0,0,1] neg_hi:[0,0,1]
	s_nop 0
	v_mov_b32_e32 v19, v9
	v_pk_add_f32 v[8:9], v[118:119], v[18:19]
	v_bfe_u32 v10, v9, 16, 1
	v_add3_u32 v10, v9, v10, s48
	global_store_short_d16_hi v[6:7], v10, off
	v_bfe_u32 v11, v8, 16, 1
	v_add3_u32 v11, v8, v11, s48
	global_store_short_d16_hi v[6:7], v11, off offset:128
	v_pk_mul_f32 v[16:17], v[0:1], v[8:9] op_sel_hi:[1,0]
	s_nop 0
	v_pk_fma_f32 v[18:19], v[2:3], v[8:9], v[16:17] op_sel:[0,1,0]
	v_pk_fma_f32 v[8:9], v[2:3], v[8:9], v[16:17] op_sel:[0,1,0] neg_lo:[0,0,1] neg_hi:[0,0,1]
	s_nop 0
	v_mov_b32_e32 v19, v9
	v_pk_add_f32 v[8:9], v[120:121], v[18:19]
	v_bfe_u32 v10, v9, 16, 1
	v_add3_u32 v10, v9, v10, s48
	global_store_short_d16_hi v[6:7], v10, off offset:256
	v_bfe_u32 v11, v8, 16, 1
	v_add3_u32 v11, v8, v11, s48
	global_store_short_d16_hi v[6:7], v11, off offset:384
	v_pk_mul_f32 v[16:17], v[0:1], v[8:9] op_sel_hi:[1,0]
	s_nop 0
	v_pk_fma_f32 v[18:19], v[2:3], v[8:9], v[16:17] op_sel:[0,1,0]
	v_pk_fma_f32 v[8:9], v[2:3], v[8:9], v[16:17] op_sel:[0,1,0] neg_lo:[0,0,1] neg_hi:[0,0,1]
	s_nop 0
	v_mov_b32_e32 v19, v9
	v_pk_add_f32 v[8:9], v[122:123], v[18:19]
	v_bfe_u32 v10, v9, 16, 1
	v_add3_u32 v10, v9, v10, s48
	global_store_short_d16_hi v[6:7], v10, off offset:512
	v_bfe_u32 v11, v8, 16, 1
	v_add3_u32 v11, v8, v11, s48
	global_store_short_d16_hi v[6:7], v11, off offset:640
	v_pk_mul_f32 v[16:17], v[0:1], v[8:9] op_sel_hi:[1,0]
	s_nop 0
	v_pk_fma_f32 v[18:19], v[2:3], v[8:9], v[16:17] op_sel:[0,1,0]
	v_pk_fma_f32 v[8:9], v[2:3], v[8:9], v[16:17] op_sel:[0,1,0] neg_lo:[0,0,1] neg_hi:[0,0,1]
	s_nop 0
	v_mov_b32_e32 v19, v9
	v_pk_add_f32 v[8:9], v[124:125], v[18:19]
	v_bfe_u32 v10, v9, 16, 1
	v_add3_u32 v10, v9, v10, s48
	global_store_short_d16_hi v[6:7], v10, off offset:768
	v_bfe_u32 v11, v8, 16, 1
	v_add3_u32 v11, v8, v11, s48
	global_store_short_d16_hi v[6:7], v11, off offset:896
	v_pk_mul_f32 v[16:17], v[0:1], v[8:9] op_sel_hi:[1,0]
	s_nop 0
	v_pk_fma_f32 v[18:19], v[2:3], v[8:9], v[16:17] op_sel:[0,1,0]
	v_pk_fma_f32 v[8:9], v[2:3], v[8:9], v[16:17] op_sel:[0,1,0] neg_lo:[0,0,1] neg_hi:[0,0,1]
	s_nop 0
	v_mov_b32_e32 v19, v9
	v_pk_add_f32 v[8:9], v[126:127], v[18:19]
	v_bfe_u32 v10, v9, 16, 1
	v_add3_u32 v10, v9, v10, s48
	global_store_short_d16_hi v[6:7], v10, off offset:1024
	v_bfe_u32 v11, v8, 16, 1
	v_add3_u32 v11, v8, v11, s48
	global_store_short_d16_hi v[6:7], v11, off offset:1152
	v_pk_mul_f32 v[16:17], v[0:1], v[8:9] op_sel_hi:[1,0]
	s_nop 0
	v_pk_fma_f32 v[18:19], v[2:3], v[8:9], v[16:17] op_sel:[0,1,0]
	v_pk_fma_f32 v[8:9], v[2:3], v[8:9], v[16:17] op_sel:[0,1,0] neg_lo:[0,0,1] neg_hi:[0,0,1]
	s_nop 0
	v_mov_b32_e32 v19, v9
	v_pk_add_f32 v[8:9], v[128:129], v[18:19]
	v_bfe_u32 v10, v9, 16, 1
	v_add3_u32 v10, v9, v10, s48
	global_store_short_d16_hi v[6:7], v10, off offset:1280
	v_bfe_u32 v11, v8, 16, 1
	v_add3_u32 v11, v8, v11, s48
	global_store_short_d16_hi v[6:7], v11, off offset:1408
	v_pk_mul_f32 v[16:17], v[0:1], v[8:9] op_sel_hi:[1,0]
	s_nop 0
	v_pk_fma_f32 v[18:19], v[2:3], v[8:9], v[16:17] op_sel:[0,1,0]
	v_pk_fma_f32 v[8:9], v[2:3], v[8:9], v[16:17] op_sel:[0,1,0] neg_lo:[0,0,1] neg_hi:[0,0,1]
	s_nop 0
	v_mov_b32_e32 v19, v9
	v_pk_add_f32 v[8:9], v[130:131], v[18:19]
	v_lshl_add_u64 v[6:7], v[6:7], 0, s[84:85]
	global_load_dword v117, v[148:149], off offset:-1024
	global_load_dword v116, v[148:149], off offset:-768
	global_load_dword v119, v[148:149], off offset:-512
	global_load_dword v118, v[148:149], off offset:-256
	global_load_dword v121, v[148:149], off
	global_load_dword v120, v[148:149], off offset:256
	global_load_dword v123, v[148:149], off offset:512
	global_load_dword v122, v[148:149], off offset:768
	global_load_dword v125, v[148:149], off offset:1024
	global_load_dword v124, v[148:149], off offset:1280
	global_load_dword v127, v[148:149], off offset:1536
	global_load_dword v126, v[148:149], off offset:1792
	global_load_dword v129, v[148:149], off offset:2048
	global_load_dword v128, v[148:149], off offset:2304
	global_load_dword v131, v[148:149], off offset:2560
	global_load_dword v130, v[148:149], off offset:2816
	v_lshl_add_u64 v[148:149], v[148:149], 0, s[100:101]
	s_waitcnt vmcnt(48)
	v_bfe_u32 v10, v9, 16, 1
	v_add3_u32 v10, v9, v10, s48
	global_store_short_d16_hi v[6:7], v10, off offset:-512
	v_bfe_u32 v11, v8, 16, 1
	v_add3_u32 v11, v8, v11, s48
	global_store_short_d16_hi v[6:7], v11, off offset:-384
	v_pk_mul_f32 v[16:17], v[0:1], v[8:9] op_sel_hi:[1,0]
	s_nop 0
	v_pk_fma_f32 v[18:19], v[2:3], v[8:9], v[16:17] op_sel:[0,1,0]
	v_pk_fma_f32 v[8:9], v[2:3], v[8:9], v[16:17] op_sel:[0,1,0] neg_lo:[0,0,1] neg_hi:[0,0,1]
	s_nop 0
	v_mov_b32_e32 v19, v9
	v_pk_add_f32 v[8:9], v[132:133], v[18:19]
	v_bfe_u32 v10, v9, 16, 1
	v_add3_u32 v10, v9, v10, s48
	global_store_short_d16_hi v[6:7], v10, off offset:-256
	v_bfe_u32 v11, v8, 16, 1
	v_add3_u32 v11, v8, v11, s48
	global_store_short_d16_hi v[6:7], v11, off offset:-128
	v_pk_mul_f32 v[16:17], v[0:1], v[8:9] op_sel_hi:[1,0]
	s_nop 0
	v_pk_fma_f32 v[18:19], v[2:3], v[8:9], v[16:17] op_sel:[0,1,0]
	v_pk_fma_f32 v[8:9], v[2:3], v[8:9], v[16:17] op_sel:[0,1,0] neg_lo:[0,0,1] neg_hi:[0,0,1]
	s_nop 0
	v_mov_b32_e32 v19, v9
	v_pk_add_f32 v[8:9], v[134:135], v[18:19]
	v_bfe_u32 v10, v9, 16, 1
	v_add3_u32 v10, v9, v10, s48
	global_store_short_d16_hi v[6:7], v10, off
	v_bfe_u32 v11, v8, 16, 1
	v_add3_u32 v11, v8, v11, s48
	global_store_short_d16_hi v[6:7], v11, off offset:128
	v_pk_mul_f32 v[16:17], v[0:1], v[8:9] op_sel_hi:[1,0]
	s_nop 0
	v_pk_fma_f32 v[18:19], v[2:3], v[8:9], v[16:17] op_sel:[0,1,0]
	v_pk_fma_f32 v[8:9], v[2:3], v[8:9], v[16:17] op_sel:[0,1,0] neg_lo:[0,0,1] neg_hi:[0,0,1]
	s_nop 0
	v_mov_b32_e32 v19, v9
	v_pk_add_f32 v[8:9], v[136:137], v[18:19]
	v_bfe_u32 v10, v9, 16, 1
	v_add3_u32 v10, v9, v10, s48
	global_store_short_d16_hi v[6:7], v10, off offset:256
	v_bfe_u32 v11, v8, 16, 1
	v_add3_u32 v11, v8, v11, s48
	global_store_short_d16_hi v[6:7], v11, off offset:384
	v_pk_mul_f32 v[16:17], v[0:1], v[8:9] op_sel_hi:[1,0]
	s_nop 0
	v_pk_fma_f32 v[18:19], v[2:3], v[8:9], v[16:17] op_sel:[0,1,0]
	v_pk_fma_f32 v[8:9], v[2:3], v[8:9], v[16:17] op_sel:[0,1,0] neg_lo:[0,0,1] neg_hi:[0,0,1]
	s_nop 0
	v_mov_b32_e32 v19, v9
	v_pk_add_f32 v[8:9], v[138:139], v[18:19]
	v_bfe_u32 v10, v9, 16, 1
	v_add3_u32 v10, v9, v10, s48
	global_store_short_d16_hi v[6:7], v10, off offset:512
	v_bfe_u32 v11, v8, 16, 1
	v_add3_u32 v11, v8, v11, s48
	global_store_short_d16_hi v[6:7], v11, off offset:640
	v_pk_mul_f32 v[16:17], v[0:1], v[8:9] op_sel_hi:[1,0]
	s_nop 0
	v_pk_fma_f32 v[18:19], v[2:3], v[8:9], v[16:17] op_sel:[0,1,0]
	v_pk_fma_f32 v[8:9], v[2:3], v[8:9], v[16:17] op_sel:[0,1,0] neg_lo:[0,0,1] neg_hi:[0,0,1]
	s_nop 0
	v_mov_b32_e32 v19, v9
	v_pk_add_f32 v[8:9], v[140:141], v[18:19]
	v_bfe_u32 v10, v9, 16, 1
	v_add3_u32 v10, v9, v10, s48
	global_store_short_d16_hi v[6:7], v10, off offset:768
	v_bfe_u32 v11, v8, 16, 1
	v_add3_u32 v11, v8, v11, s48
	global_store_short_d16_hi v[6:7], v11, off offset:896
	v_pk_mul_f32 v[16:17], v[0:1], v[8:9] op_sel_hi:[1,0]
	s_nop 0
	v_pk_fma_f32 v[18:19], v[2:3], v[8:9], v[16:17] op_sel:[0,1,0]
	v_pk_fma_f32 v[8:9], v[2:3], v[8:9], v[16:17] op_sel:[0,1,0] neg_lo:[0,0,1] neg_hi:[0,0,1]
	s_nop 0
	v_mov_b32_e32 v19, v9
	v_pk_add_f32 v[8:9], v[142:143], v[18:19]
	v_bfe_u32 v10, v9, 16, 1
	v_add3_u32 v10, v9, v10, s48
	global_store_short_d16_hi v[6:7], v10, off offset:1024
	v_bfe_u32 v11, v8, 16, 1
	v_add3_u32 v11, v8, v11, s48
	global_store_short_d16_hi v[6:7], v11, off offset:1152
	v_pk_mul_f32 v[16:17], v[0:1], v[8:9] op_sel_hi:[1,0]
	s_nop 0
	v_pk_fma_f32 v[18:19], v[2:3], v[8:9], v[16:17] op_sel:[0,1,0]
	v_pk_fma_f32 v[8:9], v[2:3], v[8:9], v[16:17] op_sel:[0,1,0] neg_lo:[0,0,1] neg_hi:[0,0,1]
	s_nop 0
	v_mov_b32_e32 v19, v9
	v_pk_add_f32 v[8:9], v[144:145], v[18:19]
	v_bfe_u32 v10, v9, 16, 1
	v_add3_u32 v10, v9, v10, s48
	global_store_short_d16_hi v[6:7], v10, off offset:1280
	v_bfe_u32 v11, v8, 16, 1
	v_add3_u32 v11, v8, v11, s48
	global_store_short_d16_hi v[6:7], v11, off offset:1408
	v_pk_mul_f32 v[16:17], v[0:1], v[8:9] op_sel_hi:[1,0]
	s_nop 0
	v_pk_fma_f32 v[18:19], v[2:3], v[8:9], v[16:17] op_sel:[0,1,0]
	v_pk_fma_f32 v[8:9], v[2:3], v[8:9], v[16:17] op_sel:[0,1,0] neg_lo:[0,0,1] neg_hi:[0,0,1]
	s_nop 0
	v_mov_b32_e32 v19, v9
	v_pk_add_f32 v[8:9], v[146:147], v[18:19]
	v_lshl_add_u64 v[6:7], v[6:7], 0, s[84:85]
	global_load_dword v133, v[148:149], off offset:-1024
	global_load_dword v132, v[148:149], off offset:-768
	global_load_dword v135, v[148:149], off offset:-512
	global_load_dword v134, v[148:149], off offset:-256
	global_load_dword v137, v[148:149], off
	global_load_dword v136, v[148:149], off offset:256
	global_load_dword v139, v[148:149], off offset:512
	global_load_dword v138, v[148:149], off offset:768
	global_load_dword v141, v[148:149], off offset:1024
	global_load_dword v140, v[148:149], off offset:1280
	global_load_dword v143, v[148:149], off offset:1536
	global_load_dword v142, v[148:149], off offset:1792
	global_load_dword v145, v[148:149], off offset:2048
	global_load_dword v144, v[148:149], off offset:2304
	global_load_dword v147, v[148:149], off offset:2560
	global_load_dword v146, v[148:149], off offset:2816
	v_lshl_add_u64 v[148:149], v[148:149], 0, s[100:101]
	s_waitcnt vmcnt(48)
	v_bfe_u32 v10, v9, 16, 1
	v_add3_u32 v10, v9, v10, s48
	global_store_short_d16_hi v[6:7], v10, off offset:-512
	v_bfe_u32 v11, v8, 16, 1
	v_add3_u32 v11, v8, v11, s48
	global_store_short_d16_hi v[6:7], v11, off offset:-384
	v_pk_mul_f32 v[16:17], v[0:1], v[8:9] op_sel_hi:[1,0]
	s_nop 0
	v_pk_fma_f32 v[18:19], v[2:3], v[8:9], v[16:17] op_sel:[0,1,0]
	v_pk_fma_f32 v[8:9], v[2:3], v[8:9], v[16:17] op_sel:[0,1,0] neg_lo:[0,0,1] neg_hi:[0,0,1]
	s_nop 0
	v_mov_b32_e32 v19, v9
	v_pk_add_f32 v[8:9], v[100:101], v[18:19]
	v_bfe_u32 v10, v9, 16, 1
	v_add3_u32 v10, v9, v10, s48
	global_store_short_d16_hi v[6:7], v10, off offset:-256
	v_bfe_u32 v11, v8, 16, 1
	v_add3_u32 v11, v8, v11, s48
	global_store_short_d16_hi v[6:7], v11, off offset:-128
	v_pk_mul_f32 v[16:17], v[0:1], v[8:9] op_sel_hi:[1,0]
	s_nop 0
	v_pk_fma_f32 v[18:19], v[2:3], v[8:9], v[16:17] op_sel:[0,1,0]
	v_pk_fma_f32 v[8:9], v[2:3], v[8:9], v[16:17] op_sel:[0,1,0] neg_lo:[0,0,1] neg_hi:[0,0,1]
	s_nop 0
	v_mov_b32_e32 v19, v9
	v_pk_add_f32 v[8:9], v[102:103], v[18:19]
	v_bfe_u32 v10, v9, 16, 1
	v_add3_u32 v10, v9, v10, s48
	global_store_short_d16_hi v[6:7], v10, off
	v_bfe_u32 v11, v8, 16, 1
	v_add3_u32 v11, v8, v11, s48
	global_store_short_d16_hi v[6:7], v11, off offset:128
	v_pk_mul_f32 v[16:17], v[0:1], v[8:9] op_sel_hi:[1,0]
	s_nop 0
	v_pk_fma_f32 v[18:19], v[2:3], v[8:9], v[16:17] op_sel:[0,1,0]
	v_pk_fma_f32 v[8:9], v[2:3], v[8:9], v[16:17] op_sel:[0,1,0] neg_lo:[0,0,1] neg_hi:[0,0,1]
	s_nop 0
	v_mov_b32_e32 v19, v9
	v_pk_add_f32 v[8:9], v[104:105], v[18:19]
	v_bfe_u32 v10, v9, 16, 1
	v_add3_u32 v10, v9, v10, s48
	global_store_short_d16_hi v[6:7], v10, off offset:256
	v_bfe_u32 v11, v8, 16, 1
	v_add3_u32 v11, v8, v11, s48
	global_store_short_d16_hi v[6:7], v11, off offset:384
	v_pk_mul_f32 v[16:17], v[0:1], v[8:9] op_sel_hi:[1,0]
	s_nop 0
	v_pk_fma_f32 v[18:19], v[2:3], v[8:9], v[16:17] op_sel:[0,1,0]
	v_pk_fma_f32 v[8:9], v[2:3], v[8:9], v[16:17] op_sel:[0,1,0] neg_lo:[0,0,1] neg_hi:[0,0,1]
	s_nop 0
	v_mov_b32_e32 v19, v9
	v_pk_add_f32 v[8:9], v[106:107], v[18:19]
	v_bfe_u32 v10, v9, 16, 1
	v_add3_u32 v10, v9, v10, s48
	global_store_short_d16_hi v[6:7], v10, off offset:512
	v_bfe_u32 v11, v8, 16, 1
	v_add3_u32 v11, v8, v11, s48
	global_store_short_d16_hi v[6:7], v11, off offset:640
	v_pk_mul_f32 v[16:17], v[0:1], v[8:9] op_sel_hi:[1,0]
	s_nop 0
	v_pk_fma_f32 v[18:19], v[2:3], v[8:9], v[16:17] op_sel:[0,1,0]
	v_pk_fma_f32 v[8:9], v[2:3], v[8:9], v[16:17] op_sel:[0,1,0] neg_lo:[0,0,1] neg_hi:[0,0,1]
	s_nop 0
	v_mov_b32_e32 v19, v9
	v_pk_add_f32 v[8:9], v[108:109], v[18:19]
	v_bfe_u32 v10, v9, 16, 1
	v_add3_u32 v10, v9, v10, s48
	global_store_short_d16_hi v[6:7], v10, off offset:768
	v_bfe_u32 v11, v8, 16, 1
	v_add3_u32 v11, v8, v11, s48
	global_store_short_d16_hi v[6:7], v11, off offset:896
	v_pk_mul_f32 v[16:17], v[0:1], v[8:9] op_sel_hi:[1,0]
	s_nop 0
	v_pk_fma_f32 v[18:19], v[2:3], v[8:9], v[16:17] op_sel:[0,1,0]
	v_pk_fma_f32 v[8:9], v[2:3], v[8:9], v[16:17] op_sel:[0,1,0] neg_lo:[0,0,1] neg_hi:[0,0,1]
	s_nop 0
	v_mov_b32_e32 v19, v9
	v_pk_add_f32 v[8:9], v[110:111], v[18:19]
	v_bfe_u32 v10, v9, 16, 1
	v_add3_u32 v10, v9, v10, s48
	global_store_short_d16_hi v[6:7], v10, off offset:1024
	v_bfe_u32 v11, v8, 16, 1
	v_add3_u32 v11, v8, v11, s48
	global_store_short_d16_hi v[6:7], v11, off offset:1152
	v_pk_mul_f32 v[16:17], v[0:1], v[8:9] op_sel_hi:[1,0]
	s_nop 0
	v_pk_fma_f32 v[18:19], v[2:3], v[8:9], v[16:17] op_sel:[0,1,0]
	v_pk_fma_f32 v[8:9], v[2:3], v[8:9], v[16:17] op_sel:[0,1,0] neg_lo:[0,0,1] neg_hi:[0,0,1]
	s_nop 0
	v_mov_b32_e32 v19, v9
	v_pk_add_f32 v[8:9], v[112:113], v[18:19]
	v_bfe_u32 v10, v9, 16, 1
	v_add3_u32 v10, v9, v10, s48
	global_store_short_d16_hi v[6:7], v10, off offset:1280
	v_bfe_u32 v11, v8, 16, 1
	v_add3_u32 v11, v8, v11, s48
	global_store_short_d16_hi v[6:7], v11, off offset:1408
	v_pk_mul_f32 v[16:17], v[0:1], v[8:9] op_sel_hi:[1,0]
	s_nop 0
	v_pk_fma_f32 v[18:19], v[2:3], v[8:9], v[16:17] op_sel:[0,1,0]
	v_pk_fma_f32 v[8:9], v[2:3], v[8:9], v[16:17] op_sel:[0,1,0] neg_lo:[0,0,1] neg_hi:[0,0,1]
	s_nop 0
	v_mov_b32_e32 v19, v9
	v_pk_add_f32 v[8:9], v[114:115], v[18:19]
	v_lshl_add_u64 v[6:7], v[6:7], 0, s[84:85]
	s_add_i32 s1, s1, 1
	s_cmp_lt_u32 s1, 4
	s_cbranch_scc1 .Lmy_s5c_loop
	global_load_dword v101, v[148:149], off offset:-1024
	global_load_dword v100, v[148:149], off offset:-768
	global_load_dword v103, v[148:149], off offset:-512
	global_load_dword v102, v[148:149], off offset:-256
	global_load_dword v105, v[148:149], off
	global_load_dword v104, v[148:149], off offset:256
	global_load_dword v107, v[148:149], off offset:512
	global_load_dword v106, v[148:149], off offset:768
	global_load_dword v109, v[148:149], off offset:1024
	global_load_dword v108, v[148:149], off offset:1280
	global_load_dword v111, v[148:149], off offset:1536
	global_load_dword v110, v[148:149], off offset:1792
	global_load_dword v113, v[148:149], off offset:2048
	global_load_dword v112, v[148:149], off offset:2304
	global_load_dword v115, v[148:149], off offset:2560
	global_load_dword v114, v[148:149], off offset:2816
	v_lshl_add_u64 v[148:149], v[148:149], 0, s[100:101]
	s_waitcnt vmcnt(63)
	v_bfe_u32 v10, v9, 16, 1
	v_add3_u32 v10, v9, v10, s48
	global_store_short_d16_hi v[6:7], v10, off offset:-512
	v_bfe_u32 v11, v8, 16, 1
	v_add3_u32 v11, v8, v11, s48
	global_store_short_d16_hi v[6:7], v11, off offset:-384
	v_pk_mul_f32 v[16:17], v[0:1], v[8:9] op_sel_hi:[1,0]
	s_nop 0
	v_pk_fma_f32 v[18:19], v[2:3], v[8:9], v[16:17] op_sel:[0,1,0]
	v_pk_fma_f32 v[8:9], v[2:3], v[8:9], v[16:17] op_sel:[0,1,0] neg_lo:[0,0,1] neg_hi:[0,0,1]
	s_nop 0
	v_mov_b32_e32 v19, v9
	v_pk_add_f32 v[8:9], v[116:117], v[18:19]
	v_bfe_u32 v10, v9, 16, 1
	v_add3_u32 v10, v9, v10, s48
	global_store_short_d16_hi v[6:7], v10, off offset:-256
	v_bfe_u32 v11, v8, 16, 1
	v_add3_u32 v11, v8, v11, s48
	global_store_short_d16_hi v[6:7], v11, off offset:-128
	v_pk_mul_f32 v[16:17], v[0:1], v[8:9] op_sel_hi:[1,0]
	s_nop 0
	v_pk_fma_f32 v[18:19], v[2:3], v[8:9], v[16:17] op_sel:[0,1,0]
	v_pk_fma_f32 v[8:9], v[2:3], v[8:9], v[16:17] op_sel:[0,1,0] neg_lo:[0,0,1] neg_hi:[0,0,1]
	s_nop 0
	v_mov_b32_e32 v19, v9
	v_pk_add_f32 v[8:9], v[118:119], v[18:19]
	v_bfe_u32 v10, v9, 16, 1
	v_add3_u32 v10, v9, v10, s48
	global_store_short_d16_hi v[6:7], v10, off
	v_bfe_u32 v11, v8, 16, 1
	v_add3_u32 v11, v8, v11, s48
	global_store_short_d16_hi v[6:7], v11, off offset:128
	v_pk_mul_f32 v[16:17], v[0:1], v[8:9] op_sel_hi:[1,0]
	s_nop 0
	v_pk_fma_f32 v[18:19], v[2:3], v[8:9], v[16:17] op_sel:[0,1,0]
	v_pk_fma_f32 v[8:9], v[2:3], v[8:9], v[16:17] op_sel:[0,1,0] neg_lo:[0,0,1] neg_hi:[0,0,1]
	s_nop 0
	v_mov_b32_e32 v19, v9
	v_pk_add_f32 v[8:9], v[120:121], v[18:19]
	v_bfe_u32 v10, v9, 16, 1
	v_add3_u32 v10, v9, v10, s48
	global_store_short_d16_hi v[6:7], v10, off offset:256
	v_bfe_u32 v11, v8, 16, 1
	v_add3_u32 v11, v8, v11, s48
	global_store_short_d16_hi v[6:7], v11, off offset:384
	v_pk_mul_f32 v[16:17], v[0:1], v[8:9] op_sel_hi:[1,0]
	s_nop 0
	v_pk_fma_f32 v[18:19], v[2:3], v[8:9], v[16:17] op_sel:[0,1,0]
	v_pk_fma_f32 v[8:9], v[2:3], v[8:9], v[16:17] op_sel:[0,1,0] neg_lo:[0,0,1] neg_hi:[0,0,1]
	s_nop 0
	v_mov_b32_e32 v19, v9
	v_pk_add_f32 v[8:9], v[122:123], v[18:19]
	v_bfe_u32 v10, v9, 16, 1
	v_add3_u32 v10, v9, v10, s48
	global_store_short_d16_hi v[6:7], v10, off offset:512
	v_bfe_u32 v11, v8, 16, 1
	v_add3_u32 v11, v8, v11, s48
	global_store_short_d16_hi v[6:7], v11, off offset:640
	v_pk_mul_f32 v[16:17], v[0:1], v[8:9] op_sel_hi:[1,0]
	s_nop 0
	v_pk_fma_f32 v[18:19], v[2:3], v[8:9], v[16:17] op_sel:[0,1,0]
	v_pk_fma_f32 v[8:9], v[2:3], v[8:9], v[16:17] op_sel:[0,1,0] neg_lo:[0,0,1] neg_hi:[0,0,1]
	s_nop 0
	v_mov_b32_e32 v19, v9
	v_pk_add_f32 v[8:9], v[124:125], v[18:19]
	v_bfe_u32 v10, v9, 16, 1
	v_add3_u32 v10, v9, v10, s48
	global_store_short_d16_hi v[6:7], v10, off offset:768
	v_bfe_u32 v11, v8, 16, 1
	v_add3_u32 v11, v8, v11, s48
	global_store_short_d16_hi v[6:7], v11, off offset:896
	v_pk_mul_f32 v[16:17], v[0:1], v[8:9] op_sel_hi:[1,0]
	s_nop 0
	v_pk_fma_f32 v[18:19], v[2:3], v[8:9], v[16:17] op_sel:[0,1,0]
	v_pk_fma_f32 v[8:9], v[2:3], v[8:9], v[16:17] op_sel:[0,1,0] neg_lo:[0,0,1] neg_hi:[0,0,1]
	s_nop 0
	v_mov_b32_e32 v19, v9
	v_pk_add_f32 v[8:9], v[126:127], v[18:19]
	v_bfe_u32 v10, v9, 16, 1
	v_add3_u32 v10, v9, v10, s48
	global_store_short_d16_hi v[6:7], v10, off offset:1024
	v_bfe_u32 v11, v8, 16, 1
	v_add3_u32 v11, v8, v11, s48
	global_store_short_d16_hi v[6:7], v11, off offset:1152
	v_pk_mul_f32 v[16:17], v[0:1], v[8:9] op_sel_hi:[1,0]
	s_nop 0
	v_pk_fma_f32 v[18:19], v[2:3], v[8:9], v[16:17] op_sel:[0,1,0]
	v_pk_fma_f32 v[8:9], v[2:3], v[8:9], v[16:17] op_sel:[0,1,0] neg_lo:[0,0,1] neg_hi:[0,0,1]
	s_nop 0
	v_mov_b32_e32 v19, v9
	v_pk_add_f32 v[8:9], v[128:129], v[18:19]
	v_bfe_u32 v10, v9, 16, 1
	v_add3_u32 v10, v9, v10, s48
	global_store_short_d16_hi v[6:7], v10, off offset:1280
	v_bfe_u32 v11, v8, 16, 1
	v_add3_u32 v11, v8, v11, s48
	global_store_short_d16_hi v[6:7], v11, off offset:1408
	v_pk_mul_f32 v[16:17], v[0:1], v[8:9] op_sel_hi:[1,0]
	s_nop 0
	v_pk_fma_f32 v[18:19], v[2:3], v[8:9], v[16:17] op_sel:[0,1,0]
	v_pk_fma_f32 v[8:9], v[2:3], v[8:9], v[16:17] op_sel:[0,1,0] neg_lo:[0,0,1] neg_hi:[0,0,1]
	s_nop 0
	v_mov_b32_e32 v19, v9
	v_pk_add_f32 v[8:9], v[130:131], v[18:19]
	v_lshl_add_u64 v[6:7], v[6:7], 0, s[84:85]
	global_load_dword v117, v[148:149], off offset:-1024
	global_load_dword v116, v[148:149], off offset:-768
	v_lshl_add_u64 v[148:149], v[148:149], 0, s[100:101]
	s_waitcnt vmcnt(50)
	v_bfe_u32 v10, v9, 16, 1
	v_add3_u32 v10, v9, v10, s48
	global_store_short_d16_hi v[6:7], v10, off offset:-512
	v_bfe_u32 v11, v8, 16, 1
	v_add3_u32 v11, v8, v11, s48
	global_store_short_d16_hi v[6:7], v11, off offset:-384
	v_pk_mul_f32 v[16:17], v[0:1], v[8:9] op_sel_hi:[1,0]
	s_nop 0
	v_pk_fma_f32 v[18:19], v[2:3], v[8:9], v[16:17] op_sel:[0,1,0]
	v_pk_fma_f32 v[8:9], v[2:3], v[8:9], v[16:17] op_sel:[0,1,0] neg_lo:[0,0,1] neg_hi:[0,0,1]
	s_nop 0
	v_mov_b32_e32 v19, v9
	v_pk_add_f32 v[8:9], v[132:133], v[18:19]
	v_bfe_u32 v10, v9, 16, 1
	v_add3_u32 v10, v9, v10, s48
	global_store_short_d16_hi v[6:7], v10, off offset:-256
	v_bfe_u32 v11, v8, 16, 1
	v_add3_u32 v11, v8, v11, s48
	global_store_short_d16_hi v[6:7], v11, off offset:-128
	v_pk_mul_f32 v[16:17], v[0:1], v[8:9] op_sel_hi:[1,0]
	s_nop 0
	v_pk_fma_f32 v[18:19], v[2:3], v[8:9], v[16:17] op_sel:[0,1,0]
	v_pk_fma_f32 v[8:9], v[2:3], v[8:9], v[16:17] op_sel:[0,1,0] neg_lo:[0,0,1] neg_hi:[0,0,1]
	s_nop 0
	v_mov_b32_e32 v19, v9
	v_pk_add_f32 v[8:9], v[134:135], v[18:19]
	v_bfe_u32 v10, v9, 16, 1
	v_add3_u32 v10, v9, v10, s48
	global_store_short_d16_hi v[6:7], v10, off
	v_bfe_u32 v11, v8, 16, 1
	v_add3_u32 v11, v8, v11, s48
	global_store_short_d16_hi v[6:7], v11, off offset:128
	v_pk_mul_f32 v[16:17], v[0:1], v[8:9] op_sel_hi:[1,0]
	s_nop 0
	v_pk_fma_f32 v[18:19], v[2:3], v[8:9], v[16:17] op_sel:[0,1,0]
	v_pk_fma_f32 v[8:9], v[2:3], v[8:9], v[16:17] op_sel:[0,1,0] neg_lo:[0,0,1] neg_hi:[0,0,1]
	s_nop 0
	v_mov_b32_e32 v19, v9
	v_pk_add_f32 v[8:9], v[136:137], v[18:19]
	v_bfe_u32 v10, v9, 16, 1
	v_add3_u32 v10, v9, v10, s48
	global_store_short_d16_hi v[6:7], v10, off offset:256
	v_bfe_u32 v11, v8, 16, 1
	v_add3_u32 v11, v8, v11, s48
	global_store_short_d16_hi v[6:7], v11, off offset:384
	v_pk_mul_f32 v[16:17], v[0:1], v[8:9] op_sel_hi:[1,0]
	s_nop 0
	v_pk_fma_f32 v[18:19], v[2:3], v[8:9], v[16:17] op_sel:[0,1,0]
	v_pk_fma_f32 v[8:9], v[2:3], v[8:9], v[16:17] op_sel:[0,1,0] neg_lo:[0,0,1] neg_hi:[0,0,1]
	s_nop 0
	v_mov_b32_e32 v19, v9
	v_pk_add_f32 v[8:9], v[138:139], v[18:19]
	v_bfe_u32 v10, v9, 16, 1
	v_add3_u32 v10, v9, v10, s48
	global_store_short_d16_hi v[6:7], v10, off offset:512
	v_bfe_u32 v11, v8, 16, 1
	v_add3_u32 v11, v8, v11, s48
	global_store_short_d16_hi v[6:7], v11, off offset:640
	v_pk_mul_f32 v[16:17], v[0:1], v[8:9] op_sel_hi:[1,0]
	s_nop 0
	v_pk_fma_f32 v[18:19], v[2:3], v[8:9], v[16:17] op_sel:[0,1,0]
	v_pk_fma_f32 v[8:9], v[2:3], v[8:9], v[16:17] op_sel:[0,1,0] neg_lo:[0,0,1] neg_hi:[0,0,1]
	s_nop 0
	v_mov_b32_e32 v19, v9
	v_pk_add_f32 v[8:9], v[140:141], v[18:19]
	v_bfe_u32 v10, v9, 16, 1
	v_add3_u32 v10, v9, v10, s48
	global_store_short_d16_hi v[6:7], v10, off offset:768
	v_bfe_u32 v11, v8, 16, 1
	v_add3_u32 v11, v8, v11, s48
	global_store_short_d16_hi v[6:7], v11, off offset:896
	v_pk_mul_f32 v[16:17], v[0:1], v[8:9] op_sel_hi:[1,0]
	s_nop 0
	v_pk_fma_f32 v[18:19], v[2:3], v[8:9], v[16:17] op_sel:[0,1,0]
	v_pk_fma_f32 v[8:9], v[2:3], v[8:9], v[16:17] op_sel:[0,1,0] neg_lo:[0,0,1] neg_hi:[0,0,1]
	s_nop 0
	v_mov_b32_e32 v19, v9
	v_pk_add_f32 v[8:9], v[142:143], v[18:19]
	v_bfe_u32 v10, v9, 16, 1
	v_add3_u32 v10, v9, v10, s48
	global_store_short_d16_hi v[6:7], v10, off offset:1024
	v_bfe_u32 v11, v8, 16, 1
	v_add3_u32 v11, v8, v11, s48
	global_store_short_d16_hi v[6:7], v11, off offset:1152
	v_pk_mul_f32 v[16:17], v[0:1], v[8:9] op_sel_hi:[1,0]
	s_nop 0
	v_pk_fma_f32 v[18:19], v[2:3], v[8:9], v[16:17] op_sel:[0,1,0]
	v_pk_fma_f32 v[8:9], v[2:3], v[8:9], v[16:17] op_sel:[0,1,0] neg_lo:[0,0,1] neg_hi:[0,0,1]
	s_nop 0
	v_mov_b32_e32 v19, v9
	v_pk_add_f32 v[8:9], v[144:145], v[18:19]
	v_bfe_u32 v10, v9, 16, 1
	v_add3_u32 v10, v9, v10, s48
	global_store_short_d16_hi v[6:7], v10, off offset:1280
	v_bfe_u32 v11, v8, 16, 1
	v_add3_u32 v11, v8, v11, s48
	global_store_short_d16_hi v[6:7], v11, off offset:1408
	v_pk_mul_f32 v[16:17], v[0:1], v[8:9] op_sel_hi:[1,0]
	s_nop 0
	v_pk_fma_f32 v[18:19], v[2:3], v[8:9], v[16:17] op_sel:[0,1,0]
	v_pk_fma_f32 v[8:9], v[2:3], v[8:9], v[16:17] op_sel:[0,1,0] neg_lo:[0,0,1] neg_hi:[0,0,1]
	s_nop 0
	v_mov_b32_e32 v19, v9
	v_pk_add_f32 v[8:9], v[146:147], v[18:19]
	v_lshl_add_u64 v[6:7], v[6:7], 0, s[84:85]
	s_waitcnt vmcnt(34)
	v_bfe_u32 v10, v9, 16, 1
	v_add3_u32 v10, v9, v10, s48
	global_store_short_d16_hi v[6:7], v10, off offset:-512
	v_bfe_u32 v11, v8, 16, 1
	v_add3_u32 v11, v8, v11, s48
	global_store_short_d16_hi v[6:7], v11, off offset:-384
	v_pk_mul_f32 v[16:17], v[0:1], v[8:9] op_sel_hi:[1,0]
	s_nop 0
	v_pk_fma_f32 v[18:19], v[2:3], v[8:9], v[16:17] op_sel:[0,1,0]
	v_pk_fma_f32 v[8:9], v[2:3], v[8:9], v[16:17] op_sel:[0,1,0] neg_lo:[0,0,1] neg_hi:[0,0,1]
	s_nop 0
	v_mov_b32_e32 v19, v9
	v_pk_add_f32 v[8:9], v[100:101], v[18:19]
	v_bfe_u32 v10, v9, 16, 1
	v_add3_u32 v10, v9, v10, s48
	global_store_short_d16_hi v[6:7], v10, off offset:-256
	v_bfe_u32 v11, v8, 16, 1
	v_add3_u32 v11, v8, v11, s48
	global_store_short_d16_hi v[6:7], v11, off offset:-128
	v_pk_mul_f32 v[16:17], v[0:1], v[8:9] op_sel_hi:[1,0]
	s_nop 0
	v_pk_fma_f32 v[18:19], v[2:3], v[8:9], v[16:17] op_sel:[0,1,0]
	v_pk_fma_f32 v[8:9], v[2:3], v[8:9], v[16:17] op_sel:[0,1,0] neg_lo:[0,0,1] neg_hi:[0,0,1]
	s_nop 0
	v_mov_b32_e32 v19, v9
	v_pk_add_f32 v[8:9], v[102:103], v[18:19]
	v_bfe_u32 v10, v9, 16, 1
	v_add3_u32 v10, v9, v10, s48
	global_store_short_d16_hi v[6:7], v10, off
	v_bfe_u32 v11, v8, 16, 1
	v_add3_u32 v11, v8, v11, s48
	global_store_short_d16_hi v[6:7], v11, off offset:128
	v_pk_mul_f32 v[16:17], v[0:1], v[8:9] op_sel_hi:[1,0]
	s_nop 0
	v_pk_fma_f32 v[18:19], v[2:3], v[8:9], v[16:17] op_sel:[0,1,0]
	v_pk_fma_f32 v[8:9], v[2:3], v[8:9], v[16:17] op_sel:[0,1,0] neg_lo:[0,0,1] neg_hi:[0,0,1]
	s_nop 0
	v_mov_b32_e32 v19, v9
	v_pk_add_f32 v[8:9], v[104:105], v[18:19]
	v_bfe_u32 v10, v9, 16, 1
	v_add3_u32 v10, v9, v10, s48
	global_store_short_d16_hi v[6:7], v10, off offset:256
	v_bfe_u32 v11, v8, 16, 1
	v_add3_u32 v11, v8, v11, s48
	global_store_short_d16_hi v[6:7], v11, off offset:384
	v_pk_mul_f32 v[16:17], v[0:1], v[8:9] op_sel_hi:[1,0]
	s_nop 0
	v_pk_fma_f32 v[18:19], v[2:3], v[8:9], v[16:17] op_sel:[0,1,0]
	v_pk_fma_f32 v[8:9], v[2:3], v[8:9], v[16:17] op_sel:[0,1,0] neg_lo:[0,0,1] neg_hi:[0,0,1]
	s_nop 0
	v_mov_b32_e32 v19, v9
	v_pk_add_f32 v[8:9], v[106:107], v[18:19]
	v_bfe_u32 v10, v9, 16, 1
	v_add3_u32 v10, v9, v10, s48
	global_store_short_d16_hi v[6:7], v10, off offset:512
	v_bfe_u32 v11, v8, 16, 1
	v_add3_u32 v11, v8, v11, s48
	global_store_short_d16_hi v[6:7], v11, off offset:640
	v_pk_mul_f32 v[16:17], v[0:1], v[8:9] op_sel_hi:[1,0]
	s_nop 0
	v_pk_fma_f32 v[18:19], v[2:3], v[8:9], v[16:17] op_sel:[0,1,0]
	v_pk_fma_f32 v[8:9], v[2:3], v[8:9], v[16:17] op_sel:[0,1,0] neg_lo:[0,0,1] neg_hi:[0,0,1]
	s_nop 0
	v_mov_b32_e32 v19, v9
	v_pk_add_f32 v[8:9], v[108:109], v[18:19]
	v_bfe_u32 v10, v9, 16, 1
	v_add3_u32 v10, v9, v10, s48
	global_store_short_d16_hi v[6:7], v10, off offset:768
	v_bfe_u32 v11, v8, 16, 1
	v_add3_u32 v11, v8, v11, s48
	global_store_short_d16_hi v[6:7], v11, off offset:896
	v_pk_mul_f32 v[16:17], v[0:1], v[8:9] op_sel_hi:[1,0]
	s_nop 0
	v_pk_fma_f32 v[18:19], v[2:3], v[8:9], v[16:17] op_sel:[0,1,0]
	v_pk_fma_f32 v[8:9], v[2:3], v[8:9], v[16:17] op_sel:[0,1,0] neg_lo:[0,0,1] neg_hi:[0,0,1]
	s_nop 0
	v_mov_b32_e32 v19, v9
	v_pk_add_f32 v[8:9], v[110:111], v[18:19]
	v_bfe_u32 v10, v9, 16, 1
	v_add3_u32 v10, v9, v10, s48
	global_store_short_d16_hi v[6:7], v10, off offset:1024
	v_bfe_u32 v11, v8, 16, 1
	v_add3_u32 v11, v8, v11, s48
	global_store_short_d16_hi v[6:7], v11, off offset:1152
	v_pk_mul_f32 v[16:17], v[0:1], v[8:9] op_sel_hi:[1,0]
	s_nop 0
	v_pk_fma_f32 v[18:19], v[2:3], v[8:9], v[16:17] op_sel:[0,1,0]
	v_pk_fma_f32 v[8:9], v[2:3], v[8:9], v[16:17] op_sel:[0,1,0] neg_lo:[0,0,1] neg_hi:[0,0,1]
	s_nop 0
	v_mov_b32_e32 v19, v9
	v_pk_add_f32 v[8:9], v[112:113], v[18:19]
	v_bfe_u32 v10, v9, 16, 1
	v_add3_u32 v10, v9, v10, s48
	global_store_short_d16_hi v[6:7], v10, off offset:1280
	v_bfe_u32 v11, v8, 16, 1
	v_add3_u32 v11, v8, v11, s48
	global_store_short_d16_hi v[6:7], v11, off offset:1408
	v_pk_mul_f32 v[16:17], v[0:1], v[8:9] op_sel_hi:[1,0]
	s_nop 0
	v_pk_fma_f32 v[18:19], v[2:3], v[8:9], v[16:17] op_sel:[0,1,0]
	v_pk_fma_f32 v[8:9], v[2:3], v[8:9], v[16:17] op_sel:[0,1,0] neg_lo:[0,0,1] neg_hi:[0,0,1]
	s_nop 0
	v_mov_b32_e32 v19, v9
	v_pk_add_f32 v[8:9], v[114:115], v[18:19]
	v_lshl_add_u64 v[6:7], v[6:7], 0, s[84:85]
	s_waitcnt vmcnt(32)
	v_bfe_u32 v10, v9, 16, 1
	v_add3_u32 v10, v9, v10, s48
	global_store_short_d16_hi v[6:7], v10, off offset:-512
	v_bfe_u32 v11, v8, 16, 1
	v_add3_u32 v11, v8, v11, s48
	global_store_short_d16_hi v[6:7], v11, off offset:-384
	v_pk_mul_f32 v[16:17], v[0:1], v[8:9] op_sel_hi:[1,0]
	s_nop 0
	v_pk_fma_f32 v[18:19], v[2:3], v[8:9], v[16:17] op_sel:[0,1,0]
	v_pk_fma_f32 v[8:9], v[2:3], v[8:9], v[16:17] op_sel:[0,1,0] neg_lo:[0,0,1] neg_hi:[0,0,1]
	s_nop 0
	v_mov_b32_e32 v19, v9
	v_pk_add_f32 v[8:9], v[116:117], v[18:19]
